# rw_finish tile v2: per-channel weights kept in registers across a virtual block's tiles, adjacent token pairs share neighbour rows in registers (24 instead of 52 loads per thread-tile)
# speedup vs baseline: 1.0067x; 1.0067x over previous
; DI int VB() { return blockIdx.x * 2 + vhalf(); }
; __global__ void __launch_bounds__(512, 2) fwd_megakernel(Params p) {
;     ...
; #pragma unroll 1
;     for (int repf = 0; repf < EXP_FIN; ++repf) {
;       const int n_rwf = MR / 16;
;       const int n_glaf = NB * 36 * 4;
;       for (int it = VB(); it < n_rwf + n_glaf; it += NVB()) {
;         if (it < n_rwf) {
;           int m0 = it * 16;
;           if (!need_ctx && (m0 % TT) >= TL) continue;
;           rw_finish_tile(p, l, it, smem);
.LBB0_998:
	s_or_b64 exec, exec, s[2:3]
	v_readfirstlane_b32 s2, v182
	s_lshr_b32 s2, s2, 8
	v_readlane_b32 s3, v252, 1
	s_barrier
	s_add_i32 s12, s2, s3
	v_writelane_b32 v253, s92, 30
	s_cmpk_gt_i32 s12, 0x11ff
	s_nop 0
	v_writelane_b32 v253, s93, 31
	s_cbranch_scc1 .LBB0_1115
	v_mov_b32_e32 v181, 0
	s_mov_b32 s71, s81
	s_lshl_b64 s[2:3], s[70:71], 2
	v_writelane_b32 v253, s2, 32
	s_nop 1
	v_writelane_b32 v253, s3, 33
	v_writelane_b32 v253, s70, 34
	s_nop 1
	v_writelane_b32 v253, s71, 35
	s_branch .LBB0_1002

; DI int otid() { int t = threadIdx.x & 255; asm volatile("" : "+v"(t)); return t; }
; DI int oidx(int i) { asm volatile("" : "+s"(i)); return i; }
; DN void rw_finish_tile(const Params& p, int l, int tile, char* smem) {
;   const bfr* P = (const bfr*)(p.ws + OFF_P);
;   const bfr* RWIN = (const bfr*)(p.ws + OFF_RWIN);
;   const bfr* Y0 = (const bfr*)(p.ws + OFF_RWY);
;   const bfr* Y1 = Y0 + (size_t)MR * 256;
;   bfr* O = (bfr*)(p.ws + OFF_HO);
;   const float* mu = p.in[oidx(10)] + (size_t)l * 2 * 1152;
;   const int tid = otid();
;   const int c0 = (tid & 31) * 8;
;   float lng[8], lnb[8], rk[8], kaw[8];
;   load8f(p.in[oidx(19)] + l * 256 + c0, lng); load8f(p.in[oidx(20)] + l * 256 + c0, lnb);
;   load8f(p.in[oidx(18)] + l * 256 + c0, rk); load8f(p.in[oidx(17)] + l * 256 + c0, kaw);
; #pragma unroll 1
;   for (int ps = 0; ps < 2; ++ps) {
;     const int m = tile * 16 + ps * 8 + (tid >> 5), t = m % TT;
;     float y0[8], y1[8], af[8], ab[8], gt[8], rr[8], kx[8], vx[8];
;     unpack8(*(const u32x4*)(Y0 + (size_t)m * 256 + c0), y0);
;     unpack8(*(const u32x4*)(Y1 + (size_t)m * 256 + c0), y1);
;     unpack8(*(const u32x4*)(RWIN + ((size_t)2 * MR + m) * 256 + c0), af);
;     unpack8(*(const u32x4*)(RWIN + ((size_t)3 * MR + m) * 256 + c0), ab);
;     unpack8(*(const u32x4*)(RWIN + ((size_t)4 * MR + m) * 256 + c0), gt);
;     shifted_load8(P, m, t, c0, mu, rr);
;     shifted_load8(P, m, t, 256 + c0, mu, kx);
;     shifted_load8(P, m, t, 512 + c0, mu, vx);
; __global__ void __launch_bounds__(512, 2) fwd_megakernel(Params p) {
;     ...
;         if (it < n_rwf) {
;           int m0 = it * 16;
;           if (!need_ctx && (m0 % TT) >= TL) continue;
;           rw_finish_tile(p, l, it, smem);
.LBB0_1093:
	s_andn2_b64 vcc, exec, s[2:3]
	s_cbranch_vccnz .LBB0_1001
	s_lshl_b32 s2, s12, 4
	s_mul_hi_i32 s3, s2, 0x38e38e39
	s_lshr_b32 s4, s3, 31
	s_ashr_i32 s3, s3, 9
	s_add_i32 s3, s3, s4
	s_mulk_i32 s3, 0x900
	s_sub_i32 s3, s2, s3
	s_cmpk_lt_i32 s3, 0x800
	s_cselect_b64 s[4:5], -1, 0
	s_or_b64 s[4:5], s[92:93], s[4:5]
	s_andn2_b64 vcc, exec, s[4:5]
	s_cbranch_vccnz .LBB0_1001
	s_load_dwordx2 s[2:3], s[0:1], 0x108
	s_load_dwordx2 s[4:5], s[0:1], 0x88
	v_readlane_b32 s8, v253, 13
	s_lshl_b32 s9, s12, 4
	s_mul_hi_u32 s98, s9, 0x38e38e39
	s_lshr_b32 s98, s98, 9
	s_mulk_i32 s98, 0x900
	s_sub_u32 s98, s9, s98
	v_and_b32_e32 v135, 31, v183
	v_lshrrev_b32_e32 v133, 5, v183
	v_lshlrev_b32_e32 v136, 4, v135
	v_lshlrev_b32_e32 v132, 5, v135
	v_lshl_add_u32 v137, v133, 1, s9
	v_mad_u32_u24 v139, v137, s88, v136
	v_add_u32_e32 v138, 0xffffe680, v139
	v_add_u32_e32 v140, 0x1980, v139
	v_add_u32_e32 v141, 0x3300, v139
	v_lshl_add_u32 v142, v137, 9, v136
	v_add_u32_e32 v143, 0x1c4fc100, v142
	v_add_u32_e32 v146, 0x17cfc100, v142
	v_add_u32_e32 v147, 0x18efc100, v142
	v_add_u32_e32 v148, 0x1a0fc100, v142
	v_add_u32_e32 v142, 0x1b2fc100, v142
	v_lshl_add_u32 v134, v137, 11, v136
	v_add_u32_e32 v134, 0x2b7c100, v134
	v_mov_b32_e32 v32, 0
	v_mov_b32_e32 v76, 0
	v_mov_b32_e32 v33, 0
	v_mov_b32_e32 v77, 0
	v_mov_b32_e32 v34, 0
	v_mov_b32_e32 v78, 0
	v_mov_b32_e32 v35, 0
	v_mov_b32_e32 v79, 0
	v_mov_b32_e32 v36, 0
	v_mov_b32_e32 v80, 0
	v_mov_b32_e32 v37, 0
	v_mov_b32_e32 v81, 0
	v_mov_b32_e32 v38, 0
	v_mov_b32_e32 v82, 0
	v_mov_b32_e32 v39, 0
	v_mov_b32_e32 v83, 0
	v_mov_b32_e32 v40, 0
	v_mov_b32_e32 v84, 0
	v_mov_b32_e32 v41, 0
	v_mov_b32_e32 v85, 0
	v_mov_b32_e32 v42, 0
	v_mov_b32_e32 v86, 0
	v_mov_b32_e32 v43, 0
	v_mov_b32_e32 v87, 0
	v_readfirstlane_b32 s99, v181
	s_lshl_b32 s9, s8, 10
	s_waitcnt lgkmcnt(0)
	s_add_u32 s4, s4, s9
	s_addc_u32 s5, s5, 0
	global_load_dwordx4 v[0:3], v142, s[2:3]
	global_load_dwordx4 v[4:7], v143, s[2:3]
	global_load_dwordx4 v[8:11], v146, s[2:3]
	global_load_dwordx4 v[12:15], v147, s[2:3]
	global_load_dwordx4 v[16:19], v148, s[2:3]
	global_load_dwordx4 v[20:23], v139, s[84:85]
	global_load_dwordx4 v[24:27], v139, s[84:85] offset:512
	global_load_dwordx4 v[28:31], v139, s[84:85] offset:1024
	v_cmp_ne_u32_e32 vcc, 0, v133
	s_andn2_b32 s6, s98, 0x800
	s_cselect_b64 vcc, exec, vcc
	s_mov_b64 exec, vcc
	global_load_dwordx4 v[32:35], v138, s[84:85]
	global_load_dwordx4 v[36:39], v138, s[84:85] offset:512
	global_load_dwordx4 v[40:43], v138, s[84:85] offset:1024
	s_mov_b64 exec, -1
	global_load_dwordx4 v[64:67], v140, s[84:85]
	global_load_dwordx4 v[68:71], v140, s[84:85] offset:512
	global_load_dwordx4 v[72:75], v140, s[84:85] offset:1024
	global_load_dwordx4 v[88:91], v132, s[4:5]
	global_load_dwordx4 v[92:95], v132, s[4:5] offset:16
	s_cmp_lg_u32 s99, 0
	s_cbranch_scc1 .Lrwf_have_w
	s_load_dwordx4 s[4:7], s[0:1], 0x90
	s_waitcnt lgkmcnt(0)
	s_add_u32 s4, s4, s9
	s_addc_u32 s5, s5, 0
	s_add_u32 s6, s6, s9
	s_addc_u32 s7, s7, 0
	global_load_dwordx4 v[172:175], v132, s[4:5]
	global_load_dwordx4 v[176:179], v132, s[4:5] offset:16
	global_load_dwordx4 v[156:159], v132, s[6:7]
	global_load_dwordx4 v[160:163], v132, s[6:7] offset:16
	s_load_dwordx2 s[4:5], s[0:1], 0xa0
	s_load_dwordx2 s[6:7], s[0:1], 0x50
	s_mulk_i32 s8, 0x2400
	s_waitcnt lgkmcnt(0)
	s_add_u32 s4, s4, s9
	s_addc_u32 s5, s5, 0
	global_load_dwordx4 v[164:167], v132, s[4:5]
	global_load_dwordx4 v[168:171], v132, s[4:5] offset:16
	s_add_u32 s4, s6, s8
	s_addc_u32 s5, s7, 0
	s_add_u32 s6, s4, 0x1200
	s_addc_u32 s7, s5, 0
	global_load_dwordx4 v[202:205], v132, s[4:5] offset:0
	global_load_dwordx4 v[206:209], v132, s[4:5] offset:16
	global_load_dwordx4 v[210:213], v132, s[6:7] offset:0
	global_load_dwordx4 v[214:217], v132, s[6:7] offset:16
	global_load_dwordx4 v[218:221], v132, s[4:5] offset:1024
	global_load_dwordx4 v[222:225], v132, s[4:5] offset:1040
	global_load_dwordx4 v[226:229], v132, s[6:7] offset:1024
	global_load_dwordx4 v[230:233], v132, s[6:7] offset:1040
	global_load_dwordx4 v[234:237], v132, s[4:5] offset:2048
	global_load_dwordx4 v[238:241], v132, s[4:5] offset:2064
	global_load_dwordx4 v[242:245], v132, s[6:7] offset:2048
	global_load_dwordx4 v[246:249], v132, s[6:7] offset:2064
	v_mov_b32_e32 v181, 1
; DI void shifted_load8(const bfr* P, int m, int t, int col, const float* mu, float (&o)[8]) {
;   const bfr* row = P + (size_t)m * PW + col;
;   const bool hp = (t != 0 && t != TL), hn = (t != TL - 1 && t != TT - 1);
;   const u32x4 cur = *(const u32x4*)row;
;   u32x4 prv = {0u, 0u, 0u, 0u}, nxt = {0u, 0u, 0u, 0u};
;   if (hp) prv = *(const u32x4*)(row - PW);
;   if (hn) nxt = *(const u32x4*)(row + PW);
;   float x[8], xp[8], xn[8], m0v[8], m1v[8];
;   unpack8(cur, x); unpack8(prv, xp); unpack8(nxt, xn);
;   load8f(mu + col, m0v); load8f(mu + 1152 + col, m1v);
; #pragma unroll
;   for (int e = 0; e < 8; ++e) o[e] = x[e] + m0v[e] * (xp[e] - x[e]) + m1v[e] * (xn[e] - x[e]);
; }
; DN void rw_finish_tile(const Params& p, int l, int tile, char* smem) {
;     ...
;     const int m = tile * 16 + ps * 8 + (tid >> 5), t = m % TT;
;     float y0[8], y1[8], af[8], ab[8], gt[8], rr[8], kx[8], vx[8];
;     unpack8(*(const u32x4*)(Y0 + (size_t)m * 256 + c0), y0);
;     unpack8(*(const u32x4*)(Y1 + (size_t)m * 256 + c0), y1);
;     unpack8(*(const u32x4*)(RWIN + ((size_t)2 * MR + m) * 256 + c0), af);
;     unpack8(*(const u32x4*)(RWIN + ((size_t)3 * MR + m) * 256 + c0), ab);
;     unpack8(*(const u32x4*)(RWIN + ((size_t)4 * MR + m) * 256 + c0), gt);
;     shifted_load8(P, m, t, c0, mu, rr);
;     shifted_load8(P, m, t, 256 + c0, mu, kx);
;     shifted_load8(P, m, t, 512 + c0, mu, vx);
.Lrwf_have_w:
	global_load_dwordx4 v[44:47], v142, s[2:3] offset:512
	global_load_dwordx4 v[48:51], v143, s[2:3] offset:512
	global_load_dwordx4 v[52:55], v146, s[2:3] offset:512
	global_load_dwordx4 v[56:59], v147, s[2:3] offset:512
	global_load_dwordx4 v[60:63], v148, s[2:3] offset:512
	v_cmp_ne_u32_e32 vcc, 7, v133
	s_sub_u32 s6, s98, 0x7f0
	s_andn2_b32 s6, s6, 0x100
	s_cselect_b64 vcc, exec, vcc
	s_mov_b64 exec, vcc
	global_load_dwordx4 v[76:79], v141, s[84:85]
	global_load_dwordx4 v[80:83], v141, s[84:85] offset:512
	global_load_dwordx4 v[84:87], v141, s[84:85] offset:1024
	s_mov_b64 exec, -1
	s_waitcnt vmcnt(8)
	v_lshlrev_b32_e32 v120, 16, v20
	v_and_b32_e32 v121, 0xffff0000, v20
	v_lshlrev_b32_e32 v122, 16, v32
	v_and_b32_e32 v123, 0xffff0000, v32
	v_lshlrev_b32_e32 v124, 16, v64
	v_and_b32_e32 v125, 0xffff0000, v64
	v_pk_add_f32 v[122:123], v[122:123], v[120:121] neg_lo:[0,1] neg_hi:[0,1]
	v_pk_add_f32 v[124:125], v[124:125], v[120:121] neg_lo:[0,1] neg_hi:[0,1]
	v_pk_fma_f32 v[120:121], v[122:123], v[202:203], v[120:121]
	v_pk_fma_f32 v[96:97], v[124:125], v[210:211], v[120:121]
	v_lshlrev_b32_e32 v120, 16, v21
	v_and_b32_e32 v121, 0xffff0000, v21
	v_lshlrev_b32_e32 v122, 16, v33
	v_and_b32_e32 v123, 0xffff0000, v33
	v_lshlrev_b32_e32 v124, 16, v65
	v_and_b32_e32 v125, 0xffff0000, v65
	v_pk_add_f32 v[122:123], v[122:123], v[120:121] neg_lo:[0,1] neg_hi:[0,1]
	v_pk_add_f32 v[124:125], v[124:125], v[120:121] neg_lo:[0,1] neg_hi:[0,1]
	v_pk_fma_f32 v[120:121], v[122:123], v[204:205], v[120:121]
	v_pk_fma_f32 v[98:99], v[124:125], v[212:213], v[120:121]
	v_lshlrev_b32_e32 v120, 16, v22
	v_and_b32_e32 v121, 0xffff0000, v22
	v_lshlrev_b32_e32 v122, 16, v34
	v_and_b32_e32 v123, 0xffff0000, v34
	v_lshlrev_b32_e32 v124, 16, v66
	v_and_b32_e32 v125, 0xffff0000, v66
	v_pk_add_f32 v[122:123], v[122:123], v[120:121] neg_lo:[0,1] neg_hi:[0,1]
	v_pk_add_f32 v[124:125], v[124:125], v[120:121] neg_lo:[0,1] neg_hi:[0,1]
	v_pk_fma_f32 v[120:121], v[122:123], v[206:207], v[120:121]
	v_pk_fma_f32 v[100:101], v[124:125], v[214:215], v[120:121]
	v_lshlrev_b32_e32 v120, 16, v23
	v_and_b32_e32 v121, 0xffff0000, v23
	v_lshlrev_b32_e32 v122, 16, v35
	v_and_b32_e32 v123, 0xffff0000, v35
	v_lshlrev_b32_e32 v124, 16, v67
	v_and_b32_e32 v125, 0xffff0000, v67
	v_pk_add_f32 v[122:123], v[122:123], v[120:121] neg_lo:[0,1] neg_hi:[0,1]
	v_pk_add_f32 v[124:125], v[124:125], v[120:121] neg_lo:[0,1] neg_hi:[0,1]
	v_pk_fma_f32 v[120:121], v[122:123], v[208:209], v[120:121]
	v_pk_fma_f32 v[102:103], v[124:125], v[216:217], v[120:121]
	v_lshlrev_b32_e32 v120, 16, v24
	v_and_b32_e32 v121, 0xffff0000, v24
	v_lshlrev_b32_e32 v122, 16, v36
	v_and_b32_e32 v123, 0xffff0000, v36
	v_lshlrev_b32_e32 v124, 16, v68
	v_and_b32_e32 v125, 0xffff0000, v68
	v_pk_add_f32 v[122:123], v[122:123], v[120:121] neg_lo:[0,1] neg_hi:[0,1]
	v_pk_add_f32 v[124:125], v[124:125], v[120:121] neg_lo:[0,1] neg_hi:[0,1]
	v_pk_fma_f32 v[120:121], v[122:123], v[218:219], v[120:121]
	v_pk_fma_f32 v[104:105], v[124:125], v[226:227], v[120:121]
	v_lshlrev_b32_e32 v120, 16, v25
	v_and_b32_e32 v121, 0xffff0000, v25
	v_lshlrev_b32_e32 v122, 16, v37
	v_and_b32_e32 v123, 0xffff0000, v37
	v_lshlrev_b32_e32 v124, 16, v69
	v_and_b32_e32 v125, 0xffff0000, v69
	v_pk_add_f32 v[122:123], v[122:123], v[120:121] neg_lo:[0,1] neg_hi:[0,1]
	v_pk_add_f32 v[124:125], v[124:125], v[120:121] neg_lo:[0,1] neg_hi:[0,1]
	v_pk_fma_f32 v[120:121], v[122:123], v[220:221], v[120:121]
	v_pk_fma_f32 v[106:107], v[124:125], v[228:229], v[120:121]
	v_lshlrev_b32_e32 v120, 16, v26
	v_and_b32_e32 v121, 0xffff0000, v26
	v_lshlrev_b32_e32 v122, 16, v38
	v_and_b32_e32 v123, 0xffff0000, v38
	v_lshlrev_b32_e32 v124, 16, v70
	v_and_b32_e32 v125, 0xffff0000, v70
	v_pk_add_f32 v[122:123], v[122:123], v[120:121] neg_lo:[0,1] neg_hi:[0,1]
	v_pk_add_f32 v[124:125], v[124:125], v[120:121] neg_lo:[0,1] neg_hi:[0,1]
	v_pk_fma_f32 v[120:121], v[122:123], v[222:223], v[120:121]
	v_pk_fma_f32 v[108:109], v[124:125], v[230:231], v[120:121]
	v_lshlrev_b32_e32 v120, 16, v27
	v_and_b32_e32 v121, 0xffff0000, v27
	v_lshlrev_b32_e32 v122, 16, v39
	v_and_b32_e32 v123, 0xffff0000, v39
	v_lshlrev_b32_e32 v124, 16, v71
	v_and_b32_e32 v125, 0xffff0000, v71
	v_pk_add_f32 v[122:123], v[122:123], v[120:121] neg_lo:[0,1] neg_hi:[0,1]
	v_pk_add_f32 v[124:125], v[124:125], v[120:121] neg_lo:[0,1] neg_hi:[0,1]
	v_pk_fma_f32 v[120:121], v[122:123], v[224:225], v[120:121]
	v_pk_fma_f32 v[110:111], v[124:125], v[232:233], v[120:121]
	v_lshlrev_b32_e32 v120, 16, v28
	v_and_b32_e32 v121, 0xffff0000, v28
	v_lshlrev_b32_e32 v122, 16, v40
	v_and_b32_e32 v123, 0xffff0000, v40
	v_lshlrev_b32_e32 v124, 16, v72
	v_and_b32_e32 v125, 0xffff0000, v72
	v_pk_add_f32 v[122:123], v[122:123], v[120:121] neg_lo:[0,1] neg_hi:[0,1]
	v_pk_add_f32 v[124:125], v[124:125], v[120:121] neg_lo:[0,1] neg_hi:[0,1]
	v_pk_fma_f32 v[120:121], v[122:123], v[234:235], v[120:121]
	v_pk_fma_f32 v[112:113], v[124:125], v[242:243], v[120:121]
	v_lshlrev_b32_e32 v120, 16, v29
	v_and_b32_e32 v121, 0xffff0000, v29
	v_lshlrev_b32_e32 v122, 16, v41
	v_and_b32_e32 v123, 0xffff0000, v41
	v_lshlrev_b32_e32 v124, 16, v73
	v_and_b32_e32 v125, 0xffff0000, v73
	v_pk_add_f32 v[122:123], v[122:123], v[120:121] neg_lo:[0,1] neg_hi:[0,1]
	v_pk_add_f32 v[124:125], v[124:125], v[120:121] neg_lo:[0,1] neg_hi:[0,1]
	v_pk_fma_f32 v[120:121], v[122:123], v[236:237], v[120:121]
	v_pk_fma_f32 v[114:115], v[124:125], v[244:245], v[120:121]
	v_lshlrev_b32_e32 v120, 16, v30
	v_and_b32_e32 v121, 0xffff0000, v30
	v_lshlrev_b32_e32 v122, 16, v42
	v_and_b32_e32 v123, 0xffff0000, v42
	v_lshlrev_b32_e32 v124, 16, v74
	v_and_b32_e32 v125, 0xffff0000, v74
; DI float red8(float x) { x += dppf<0xB1>(x); x += dppf<0x4E>(x); x += dppf<0x141>(x); return x; }
; DN void rw_finish_tile(const Params& p, int l, int tile, char* smem) {
;     ...
;     float sy = 0.f;
; #pragma unroll
;     for (int e = 0; e < 8; ++e) { y0[e] += y1[e]; sy += y0[e]; }
;     const float mean = red8(sy) * (1.f / 64.f);
;     float sv = 0.f, sd = 0.f;
; #pragma unroll
;     for (int e = 0; e < 8; ++e) {
;       const float dl = y0[e] - mean; y0[e] = dl; sv += dl * dl;
;       const float kds = kx[e] * (1.f + (af[e] - 1.f) * kaw[e]) + kx[e] * (1.f + (ab[e] - 1.f) * kaw[e]);
;       sd += rr[e] * rk[e] * kds;
;     }
;     const float var = red8(sv) * (1.f / 64.f);
;     const float sdot = red8(sd);
	v_pk_add_f32 v[122:123], v[122:123], v[120:121] neg_lo:[0,1] neg_hi:[0,1]
	v_pk_add_f32 v[124:125], v[124:125], v[120:121] neg_lo:[0,1] neg_hi:[0,1]
	v_pk_fma_f32 v[120:121], v[122:123], v[238:239], v[120:121]
	v_pk_fma_f32 v[116:117], v[124:125], v[246:247], v[120:121]
	v_lshlrev_b32_e32 v120, 16, v31
	v_and_b32_e32 v121, 0xffff0000, v31
	v_lshlrev_b32_e32 v122, 16, v43
	v_and_b32_e32 v123, 0xffff0000, v43
	v_lshlrev_b32_e32 v124, 16, v75
	v_and_b32_e32 v125, 0xffff0000, v75
	v_pk_add_f32 v[122:123], v[122:123], v[120:121] neg_lo:[0,1] neg_hi:[0,1]
	v_pk_add_f32 v[124:125], v[124:125], v[120:121] neg_lo:[0,1] neg_hi:[0,1]
	v_pk_fma_f32 v[120:121], v[122:123], v[240:241], v[120:121]
	v_pk_fma_f32 v[118:119], v[124:125], v[248:249], v[120:121]
	v_lshlrev_b32_e32 v120, 16, v0
	v_and_b32_e32 v121, 0xffff0000, v0
	v_lshlrev_b32_e32 v122, 16, v4
	v_and_b32_e32 v123, 0xffff0000, v4
	v_pk_add_f32 v[32:33], v[120:121], v[122:123]
	v_lshlrev_b32_e32 v120, 16, v1
	v_and_b32_e32 v121, 0xffff0000, v1
	v_lshlrev_b32_e32 v122, 16, v5
	v_and_b32_e32 v123, 0xffff0000, v5
	v_pk_add_f32 v[34:35], v[120:121], v[122:123]
	v_lshlrev_b32_e32 v120, 16, v2
	v_and_b32_e32 v121, 0xffff0000, v2
	v_lshlrev_b32_e32 v122, 16, v6
	v_and_b32_e32 v123, 0xffff0000, v6
	v_pk_add_f32 v[36:37], v[120:121], v[122:123]
	v_lshlrev_b32_e32 v120, 16, v3
	v_and_b32_e32 v121, 0xffff0000, v3
	v_lshlrev_b32_e32 v122, 16, v7
	v_and_b32_e32 v123, 0xffff0000, v7
	v_pk_add_f32 v[38:39], v[120:121], v[122:123]
	v_add_f32_e32 v126, 0, v32
	v_add_f32_e32 v126, v33, v126
	v_add_f32_e32 v126, v34, v126
	v_add_f32_e32 v126, v35, v126
	v_add_f32_e32 v126, v36, v126
	v_add_f32_e32 v126, v37, v126
	v_add_f32_e32 v126, v38, v126
	v_add_f32_e32 v126, v39, v126
	s_nop 1
	v_add_f32_dpp v126, v126, v126 quad_perm:[1,0,3,2] row_mask:0xf bank_mask:0xf bound_ctrl:1
	s_nop 1
	v_add_f32_dpp v126, v126, v126 quad_perm:[2,3,0,1] row_mask:0xf bank_mask:0xf bound_ctrl:1
	s_nop 1
	v_add_f32_dpp v126, v126, v126 row_half_mirror row_mask:0xf bank_mask:0xf bound_ctrl:1
	v_mul_f32_e32 v128, 0x3c800000, v126
	v_pk_add_f32 v[32:33], v[32:33], v[128:129] op_sel_hi:[1,0] neg_lo:[0,1] neg_hi:[0,1]
	v_pk_add_f32 v[34:35], v[34:35], v[128:129] op_sel_hi:[1,0] neg_lo:[0,1] neg_hi:[0,1]
	v_pk_add_f32 v[36:37], v[36:37], v[128:129] op_sel_hi:[1,0] neg_lo:[0,1] neg_hi:[0,1]
	v_pk_add_f32 v[38:39], v[38:39], v[128:129] op_sel_hi:[1,0] neg_lo:[0,1] neg_hi:[0,1]
	v_pk_mul_f32 v[120:121], v[32:33], v[32:33]
	v_add_f32_e32 v130, 0, v120
	v_add_f32_e32 v130, v121, v130
	v_pk_mul_f32 v[120:121], v[34:35], v[34:35]
	v_add_f32_e32 v130, v120, v130
	v_add_f32_e32 v130, v121, v130
	v_pk_mul_f32 v[120:121], v[36:37], v[36:37]
	v_add_f32_e32 v130, v120, v130
	v_add_f32_e32 v130, v121, v130
	v_pk_mul_f32 v[120:121], v[38:39], v[38:39]
	v_add_f32_e32 v130, v120, v130
	v_add_f32_e32 v130, v121, v130
	v_lshlrev_b32_e32 v120, 16, v8
	v_and_b32_e32 v121, 0xffff0000, v8
	v_lshlrev_b32_e32 v122, 16, v12
	v_and_b32_e32 v123, 0xffff0000, v12
	v_pk_add_f32 v[120:121], v[120:121], -1.0 op_sel_hi:[1,0]
	v_pk_add_f32 v[122:123], v[122:123], -1.0 op_sel_hi:[1,0]
	v_pk_fma_f32 v[120:121], v[88:89], v[120:121], 1.0 op_sel_hi:[1,1,0]
	v_pk_fma_f32 v[122:123], v[88:89], v[122:123], 1.0 op_sel_hi:[1,1,0]
	v_pk_mul_f32 v[120:121], v[120:121], v[104:105]
	v_pk_fma_f32 v[122:123], v[122:123], v[104:105], v[120:121]
	v_pk_mul_f32 v[124:125], v[172:173], v[96:97]
	v_pk_mul_f32 v[124:125], v[124:125], v[122:123]
	v_add_f32_e32 v131, 0, v124
	v_add_f32_e32 v131, v125, v131
	v_lshlrev_b32_e32 v120, 16, v9
	v_and_b32_e32 v121, 0xffff0000, v9
	v_lshlrev_b32_e32 v122, 16, v13
	v_and_b32_e32 v123, 0xffff0000, v13
	v_pk_add_f32 v[120:121], v[120:121], -1.0 op_sel_hi:[1,0]
	v_pk_add_f32 v[122:123], v[122:123], -1.0 op_sel_hi:[1,0]
	v_pk_fma_f32 v[120:121], v[90:91], v[120:121], 1.0 op_sel_hi:[1,1,0]
	v_pk_fma_f32 v[122:123], v[90:91], v[122:123], 1.0 op_sel_hi:[1,1,0]
	v_pk_mul_f32 v[120:121], v[120:121], v[106:107]
	v_pk_fma_f32 v[122:123], v[122:123], v[106:107], v[120:121]
	v_pk_mul_f32 v[124:125], v[174:175], v[98:99]
	v_pk_mul_f32 v[124:125], v[124:125], v[122:123]
	v_add_f32_e32 v131, v124, v131
	v_add_f32_e32 v131, v125, v131
	v_lshlrev_b32_e32 v120, 16, v10
	v_and_b32_e32 v121, 0xffff0000, v10
	v_lshlrev_b32_e32 v122, 16, v14
	v_and_b32_e32 v123, 0xffff0000, v14
	v_pk_add_f32 v[120:121], v[120:121], -1.0 op_sel_hi:[1,0]
	v_pk_add_f32 v[122:123], v[122:123], -1.0 op_sel_hi:[1,0]
	v_pk_fma_f32 v[120:121], v[92:93], v[120:121], 1.0 op_sel_hi:[1,1,0]
	v_pk_fma_f32 v[122:123], v[92:93], v[122:123], 1.0 op_sel_hi:[1,1,0]
	v_pk_mul_f32 v[120:121], v[120:121], v[108:109]
	v_pk_fma_f32 v[122:123], v[122:123], v[108:109], v[120:121]
	v_pk_mul_f32 v[124:125], v[176:177], v[100:101]
	v_pk_mul_f32 v[124:125], v[124:125], v[122:123]
	v_add_f32_e32 v131, v124, v131
	v_add_f32_e32 v131, v125, v131
	v_lshlrev_b32_e32 v120, 16, v11
	v_and_b32_e32 v121, 0xffff0000, v11
	v_lshlrev_b32_e32 v122, 16, v15
	v_and_b32_e32 v123, 0xffff0000, v15
	v_pk_add_f32 v[120:121], v[120:121], -1.0 op_sel_hi:[1,0]
	v_pk_add_f32 v[122:123], v[122:123], -1.0 op_sel_hi:[1,0]
	v_pk_fma_f32 v[120:121], v[94:95], v[120:121], 1.0 op_sel_hi:[1,1,0]
	v_pk_fma_f32 v[122:123], v[94:95], v[122:123], 1.0 op_sel_hi:[1,1,0]
	v_pk_mul_f32 v[120:121], v[120:121], v[110:111]
	v_pk_fma_f32 v[122:123], v[122:123], v[110:111], v[120:121]
	v_pk_mul_f32 v[124:125], v[178:179], v[102:103]
	v_pk_mul_f32 v[124:125], v[124:125], v[122:123]
	v_add_f32_e32 v131, v124, v131
	v_add_f32_e32 v131, v125, v131
	v_add_f32_dpp v130, v130, v130 quad_perm:[1,0,3,2] row_mask:0xf bank_mask:0xf bound_ctrl:1
	s_nop 0
; DI unsigned pack2(float a, float b) { unsigned r; asm volatile("v_cvt_pk_bf16_f32 %0, %1, %2" : "=v"(r) : "v"(a), "v"(b)); return r; }
; DI void shifted_load8(const bfr* P, int m, int t, int col, const float* mu, float (&o)[8]) {
;   const bfr* row = P + (size_t)m * PW + col;
;   const bool hp = (t != 0 && t != TL), hn = (t != TL - 1 && t != TT - 1);
;   const u32x4 cur = *(const u32x4*)row;
;   u32x4 prv = {0u, 0u, 0u, 0u}, nxt = {0u, 0u, 0u, 0u};
;   if (hp) prv = *(const u32x4*)(row - PW);
;   if (hn) nxt = *(const u32x4*)(row + PW);
;   float x[8], xp[8], xn[8], m0v[8], m1v[8];
;   unpack8(cur, x); unpack8(prv, xp); unpack8(nxt, xn);
;   load8f(mu + col, m0v); load8f(mu + 1152 + col, m1v);
; #pragma unroll
;   for (int e = 0; e < 8; ++e) o[e] = x[e] + m0v[e] * (xp[e] - x[e]) + m1v[e] * (xn[e] - x[e]);
; }
; DN void rw_finish_tile(const Params& p, int l, int tile, char* smem) {
;     ...
;     const float rs = rsqrtf(var + 64e-5f);
;     float ov[8];
; #pragma unroll
;     for (int e = 0; e < 8; ++e) ov[e] = (y0[e] * rs * lng[e] + lnb[e] + sdot * vx[e]) * gt[e];
;     u32x4 ow; ow.x = pack2(ov[0], ov[1]); ow.y = pack2(ov[2], ov[3]); ow.z = pack2(ov[4], ov[5]); ow.w = pack2(ov[6], ov[7]);
;     *(u32x4*)(O + (size_t)m * DM + c0) = ow;
	v_add_f32_dpp v131, v131, v131 quad_perm:[1,0,3,2] row_mask:0xf bank_mask:0xf bound_ctrl:1
	v_add_f32_dpp v130, v130, v130 quad_perm:[2,3,0,1] row_mask:0xf bank_mask:0xf bound_ctrl:1
	s_nop 0
	v_add_f32_dpp v131, v131, v131 quad_perm:[2,3,0,1] row_mask:0xf bank_mask:0xf bound_ctrl:1
	v_add_f32_dpp v130, v130, v130 row_half_mirror row_mask:0xf bank_mask:0xf bound_ctrl:1
	s_nop 0
	v_add_f32_dpp v131, v131, v131 row_half_mirror row_mask:0xf bank_mask:0xf bound_ctrl:1
	v_mov_b32_e32 v129, 0x3a27c5ac
	v_fmamk_f32 v130, v130, 0x3c800000, v129
	v_rsq_f32_e32 v130, v130
	v_mov_b32_e32 v126, v131
	v_pk_mul_f32 v[120:121], v[32:33], v[130:131] op_sel_hi:[1,0]
	v_pk_mul_f32 v[120:121], v[156:157], v[120:121]
	v_pk_add_f32 v[120:121], v[164:165], v[120:121]
	v_pk_mul_f32 v[122:123], v[112:113], v[126:127] op_sel_hi:[1,0]
	v_pk_add_f32 v[120:121], v[122:123], v[120:121]
	v_lshlrev_b32_e32 v122, 16, v16
	v_and_b32_e32 v123, 0xffff0000, v16
	v_pk_mul_f32 v[120:121], v[120:121], v[122:123]
	v_cvt_pk_bf16_f32 v16, v120, v121
	v_pk_mul_f32 v[120:121], v[34:35], v[130:131] op_sel_hi:[1,0]
	v_pk_mul_f32 v[120:121], v[158:159], v[120:121]
	v_pk_add_f32 v[120:121], v[166:167], v[120:121]
	v_pk_mul_f32 v[122:123], v[114:115], v[126:127] op_sel_hi:[1,0]
	v_pk_add_f32 v[120:121], v[122:123], v[120:121]
	v_lshlrev_b32_e32 v122, 16, v17
	v_and_b32_e32 v123, 0xffff0000, v17
	v_pk_mul_f32 v[120:121], v[120:121], v[122:123]
	v_cvt_pk_bf16_f32 v17, v120, v121
	v_pk_mul_f32 v[120:121], v[36:37], v[130:131] op_sel_hi:[1,0]
	v_pk_mul_f32 v[120:121], v[160:161], v[120:121]
	v_pk_add_f32 v[120:121], v[168:169], v[120:121]
	v_pk_mul_f32 v[122:123], v[116:117], v[126:127] op_sel_hi:[1,0]
	v_pk_add_f32 v[120:121], v[122:123], v[120:121]
	v_lshlrev_b32_e32 v122, 16, v18
	v_and_b32_e32 v123, 0xffff0000, v18
	v_pk_mul_f32 v[120:121], v[120:121], v[122:123]
	v_cvt_pk_bf16_f32 v18, v120, v121
	v_pk_mul_f32 v[120:121], v[38:39], v[130:131] op_sel_hi:[1,0]
	v_pk_mul_f32 v[120:121], v[162:163], v[120:121]
	v_pk_add_f32 v[120:121], v[170:171], v[120:121]
	v_pk_mul_f32 v[122:123], v[118:119], v[126:127] op_sel_hi:[1,0]
	v_pk_add_f32 v[120:121], v[122:123], v[120:121]
	v_lshlrev_b32_e32 v122, 16, v19
	v_and_b32_e32 v123, 0xffff0000, v19
	v_pk_mul_f32 v[120:121], v[120:121], v[122:123]
	v_cvt_pk_bf16_f32 v19, v120, v121
	global_store_dwordx4 v134, v[16:19], s[2:3]
	s_waitcnt vmcnt(1)
	v_lshlrev_b32_e32 v120, 16, v64
	v_and_b32_e32 v121, 0xffff0000, v64
	v_lshlrev_b32_e32 v122, 16, v20
	v_and_b32_e32 v123, 0xffff0000, v20
	v_lshlrev_b32_e32 v124, 16, v76
	v_and_b32_e32 v125, 0xffff0000, v76
	v_pk_add_f32 v[122:123], v[122:123], v[120:121] neg_lo:[0,1] neg_hi:[0,1]
	v_pk_add_f32 v[124:125], v[124:125], v[120:121] neg_lo:[0,1] neg_hi:[0,1]
	v_pk_fma_f32 v[120:121], v[122:123], v[202:203], v[120:121]
	v_pk_fma_f32 v[96:97], v[124:125], v[210:211], v[120:121]
	v_lshlrev_b32_e32 v120, 16, v65
	v_and_b32_e32 v121, 0xffff0000, v65
	v_lshlrev_b32_e32 v122, 16, v21
	v_and_b32_e32 v123, 0xffff0000, v21
	v_lshlrev_b32_e32 v124, 16, v77
	v_and_b32_e32 v125, 0xffff0000, v77
	v_pk_add_f32 v[122:123], v[122:123], v[120:121] neg_lo:[0,1] neg_hi:[0,1]
	v_pk_add_f32 v[124:125], v[124:125], v[120:121] neg_lo:[0,1] neg_hi:[0,1]
	v_pk_fma_f32 v[120:121], v[122:123], v[204:205], v[120:121]
	v_pk_fma_f32 v[98:99], v[124:125], v[212:213], v[120:121]
	v_lshlrev_b32_e32 v120, 16, v66
	v_and_b32_e32 v121, 0xffff0000, v66
	v_lshlrev_b32_e32 v122, 16, v22
	v_and_b32_e32 v123, 0xffff0000, v22
	v_lshlrev_b32_e32 v124, 16, v78
	v_and_b32_e32 v125, 0xffff0000, v78
	v_pk_add_f32 v[122:123], v[122:123], v[120:121] neg_lo:[0,1] neg_hi:[0,1]
	v_pk_add_f32 v[124:125], v[124:125], v[120:121] neg_lo:[0,1] neg_hi:[0,1]
	v_pk_fma_f32 v[120:121], v[122:123], v[206:207], v[120:121]
	v_pk_fma_f32 v[100:101], v[124:125], v[214:215], v[120:121]
	v_lshlrev_b32_e32 v120, 16, v67
	v_and_b32_e32 v121, 0xffff0000, v67
	v_lshlrev_b32_e32 v122, 16, v23
	v_and_b32_e32 v123, 0xffff0000, v23
	v_lshlrev_b32_e32 v124, 16, v79
	v_and_b32_e32 v125, 0xffff0000, v79
	v_pk_add_f32 v[122:123], v[122:123], v[120:121] neg_lo:[0,1] neg_hi:[0,1]
	v_pk_add_f32 v[124:125], v[124:125], v[120:121] neg_lo:[0,1] neg_hi:[0,1]
	v_pk_fma_f32 v[120:121], v[122:123], v[208:209], v[120:121]
	v_pk_fma_f32 v[102:103], v[124:125], v[216:217], v[120:121]
	v_lshlrev_b32_e32 v120, 16, v68
	v_and_b32_e32 v121, 0xffff0000, v68
	v_lshlrev_b32_e32 v122, 16, v24
	v_and_b32_e32 v123, 0xffff0000, v24
	v_lshlrev_b32_e32 v124, 16, v80
	v_and_b32_e32 v125, 0xffff0000, v80
	v_pk_add_f32 v[122:123], v[122:123], v[120:121] neg_lo:[0,1] neg_hi:[0,1]
	v_pk_add_f32 v[124:125], v[124:125], v[120:121] neg_lo:[0,1] neg_hi:[0,1]
	v_pk_fma_f32 v[120:121], v[122:123], v[218:219], v[120:121]
	v_pk_fma_f32 v[104:105], v[124:125], v[226:227], v[120:121]
	v_lshlrev_b32_e32 v120, 16, v69
	v_and_b32_e32 v121, 0xffff0000, v69
	v_lshlrev_b32_e32 v122, 16, v25
	v_and_b32_e32 v123, 0xffff0000, v25
	v_lshlrev_b32_e32 v124, 16, v81
	v_and_b32_e32 v125, 0xffff0000, v81
	v_pk_add_f32 v[122:123], v[122:123], v[120:121] neg_lo:[0,1] neg_hi:[0,1]
	v_pk_add_f32 v[124:125], v[124:125], v[120:121] neg_lo:[0,1] neg_hi:[0,1]
	v_pk_fma_f32 v[120:121], v[122:123], v[220:221], v[120:121]
	v_pk_fma_f32 v[106:107], v[124:125], v[228:229], v[120:121]
	v_lshlrev_b32_e32 v120, 16, v70
	v_and_b32_e32 v121, 0xffff0000, v70
	v_lshlrev_b32_e32 v122, 16, v26
	v_and_b32_e32 v123, 0xffff0000, v26
	v_lshlrev_b32_e32 v124, 16, v82
	v_and_b32_e32 v125, 0xffff0000, v82
	v_pk_add_f32 v[122:123], v[122:123], v[120:121] neg_lo:[0,1] neg_hi:[0,1]
	v_pk_add_f32 v[124:125], v[124:125], v[120:121] neg_lo:[0,1] neg_hi:[0,1]
; DI float red8(float x) { x += dppf<0xB1>(x); x += dppf<0x4E>(x); x += dppf<0x141>(x); return x; }
; DI void shifted_load8(const bfr* P, int m, int t, int col, const float* mu, float (&o)[8]) {
;   const bfr* row = P + (size_t)m * PW + col;
;   const bool hp = (t != 0 && t != TL), hn = (t != TL - 1 && t != TT - 1);
;   const u32x4 cur = *(const u32x4*)row;
;   u32x4 prv = {0u, 0u, 0u, 0u}, nxt = {0u, 0u, 0u, 0u};
;   if (hp) prv = *(const u32x4*)(row - PW);
;   if (hn) nxt = *(const u32x4*)(row + PW);
;   float x[8], xp[8], xn[8], m0v[8], m1v[8];
;   unpack8(cur, x); unpack8(prv, xp); unpack8(nxt, xn);
;   load8f(mu + col, m0v); load8f(mu + 1152 + col, m1v);
; #pragma unroll
;   for (int e = 0; e < 8; ++e) o[e] = x[e] + m0v[e] * (xp[e] - x[e]) + m1v[e] * (xn[e] - x[e]);
; }
; DN void rw_finish_tile(const Params& p, int l, int tile, char* smem) {
;     ...
;     float sy = 0.f;
; #pragma unroll
;     for (int e = 0; e < 8; ++e) { y0[e] += y1[e]; sy += y0[e]; }
;     const float mean = red8(sy) * (1.f / 64.f);
;     float sv = 0.f, sd = 0.f;
; #pragma unroll
;     for (int e = 0; e < 8; ++e) {
;       const float dl = y0[e] - mean; y0[e] = dl; sv += dl * dl;
;       const float kds = kx[e] * (1.f + (af[e] - 1.f) * kaw[e]) + kx[e] * (1.f + (ab[e] - 1.f) * kaw[e]);
;       sd += rr[e] * rk[e] * kds;
	v_pk_fma_f32 v[120:121], v[122:123], v[222:223], v[120:121]
	v_pk_fma_f32 v[108:109], v[124:125], v[230:231], v[120:121]
	v_lshlrev_b32_e32 v120, 16, v71
	v_and_b32_e32 v121, 0xffff0000, v71
	v_lshlrev_b32_e32 v122, 16, v27
	v_and_b32_e32 v123, 0xffff0000, v27
	v_lshlrev_b32_e32 v124, 16, v83
	v_and_b32_e32 v125, 0xffff0000, v83
	v_pk_add_f32 v[122:123], v[122:123], v[120:121] neg_lo:[0,1] neg_hi:[0,1]
	v_pk_add_f32 v[124:125], v[124:125], v[120:121] neg_lo:[0,1] neg_hi:[0,1]
	v_pk_fma_f32 v[120:121], v[122:123], v[224:225], v[120:121]
	v_pk_fma_f32 v[110:111], v[124:125], v[232:233], v[120:121]
	v_lshlrev_b32_e32 v120, 16, v72
	v_and_b32_e32 v121, 0xffff0000, v72
	v_lshlrev_b32_e32 v122, 16, v28
	v_and_b32_e32 v123, 0xffff0000, v28
	v_lshlrev_b32_e32 v124, 16, v84
	v_and_b32_e32 v125, 0xffff0000, v84
	v_pk_add_f32 v[122:123], v[122:123], v[120:121] neg_lo:[0,1] neg_hi:[0,1]
	v_pk_add_f32 v[124:125], v[124:125], v[120:121] neg_lo:[0,1] neg_hi:[0,1]
	v_pk_fma_f32 v[120:121], v[122:123], v[234:235], v[120:121]
	v_pk_fma_f32 v[112:113], v[124:125], v[242:243], v[120:121]
	v_lshlrev_b32_e32 v120, 16, v73
	v_and_b32_e32 v121, 0xffff0000, v73
	v_lshlrev_b32_e32 v122, 16, v29
	v_and_b32_e32 v123, 0xffff0000, v29
	v_lshlrev_b32_e32 v124, 16, v85
	v_and_b32_e32 v125, 0xffff0000, v85
	v_pk_add_f32 v[122:123], v[122:123], v[120:121] neg_lo:[0,1] neg_hi:[0,1]
	v_pk_add_f32 v[124:125], v[124:125], v[120:121] neg_lo:[0,1] neg_hi:[0,1]
	v_pk_fma_f32 v[120:121], v[122:123], v[236:237], v[120:121]
	v_pk_fma_f32 v[114:115], v[124:125], v[244:245], v[120:121]
	v_lshlrev_b32_e32 v120, 16, v74
	v_and_b32_e32 v121, 0xffff0000, v74
	v_lshlrev_b32_e32 v122, 16, v30
	v_and_b32_e32 v123, 0xffff0000, v30
	v_lshlrev_b32_e32 v124, 16, v86
	v_and_b32_e32 v125, 0xffff0000, v86
	v_pk_add_f32 v[122:123], v[122:123], v[120:121] neg_lo:[0,1] neg_hi:[0,1]
	v_pk_add_f32 v[124:125], v[124:125], v[120:121] neg_lo:[0,1] neg_hi:[0,1]
	v_pk_fma_f32 v[120:121], v[122:123], v[238:239], v[120:121]
	v_pk_fma_f32 v[116:117], v[124:125], v[246:247], v[120:121]
	v_lshlrev_b32_e32 v120, 16, v75
	v_and_b32_e32 v121, 0xffff0000, v75
	v_lshlrev_b32_e32 v122, 16, v31
	v_and_b32_e32 v123, 0xffff0000, v31
	v_lshlrev_b32_e32 v124, 16, v87
	v_and_b32_e32 v125, 0xffff0000, v87
	v_pk_add_f32 v[122:123], v[122:123], v[120:121] neg_lo:[0,1] neg_hi:[0,1]
	v_pk_add_f32 v[124:125], v[124:125], v[120:121] neg_lo:[0,1] neg_hi:[0,1]
	v_pk_fma_f32 v[120:121], v[122:123], v[240:241], v[120:121]
	v_pk_fma_f32 v[118:119], v[124:125], v[248:249], v[120:121]
	v_lshlrev_b32_e32 v120, 16, v44
	v_and_b32_e32 v121, 0xffff0000, v44
	v_lshlrev_b32_e32 v122, 16, v48
	v_and_b32_e32 v123, 0xffff0000, v48
	v_pk_add_f32 v[76:77], v[120:121], v[122:123]
	v_lshlrev_b32_e32 v120, 16, v45
	v_and_b32_e32 v121, 0xffff0000, v45
	v_lshlrev_b32_e32 v122, 16, v49
	v_and_b32_e32 v123, 0xffff0000, v49
	v_pk_add_f32 v[78:79], v[120:121], v[122:123]
	v_lshlrev_b32_e32 v120, 16, v46
	v_and_b32_e32 v121, 0xffff0000, v46
	v_lshlrev_b32_e32 v122, 16, v50
	v_and_b32_e32 v123, 0xffff0000, v50
	v_pk_add_f32 v[80:81], v[120:121], v[122:123]
	v_lshlrev_b32_e32 v120, 16, v47
	v_and_b32_e32 v121, 0xffff0000, v47
	v_lshlrev_b32_e32 v122, 16, v51
	v_and_b32_e32 v123, 0xffff0000, v51
	v_pk_add_f32 v[82:83], v[120:121], v[122:123]
	v_add_f32_e32 v126, 0, v76
	v_add_f32_e32 v126, v77, v126
	v_add_f32_e32 v126, v78, v126
	v_add_f32_e32 v126, v79, v126
	v_add_f32_e32 v126, v80, v126
	v_add_f32_e32 v126, v81, v126
	v_add_f32_e32 v126, v82, v126
	v_add_f32_e32 v126, v83, v126
	s_nop 1
	v_add_f32_dpp v126, v126, v126 quad_perm:[1,0,3,2] row_mask:0xf bank_mask:0xf bound_ctrl:1
	s_nop 1
	v_add_f32_dpp v126, v126, v126 quad_perm:[2,3,0,1] row_mask:0xf bank_mask:0xf bound_ctrl:1
	s_nop 1
	v_add_f32_dpp v126, v126, v126 row_half_mirror row_mask:0xf bank_mask:0xf bound_ctrl:1
	v_mul_f32_e32 v128, 0x3c800000, v126
	v_pk_add_f32 v[76:77], v[76:77], v[128:129] op_sel_hi:[1,0] neg_lo:[0,1] neg_hi:[0,1]
	v_pk_add_f32 v[78:79], v[78:79], v[128:129] op_sel_hi:[1,0] neg_lo:[0,1] neg_hi:[0,1]
	v_pk_add_f32 v[80:81], v[80:81], v[128:129] op_sel_hi:[1,0] neg_lo:[0,1] neg_hi:[0,1]
	v_pk_add_f32 v[82:83], v[82:83], v[128:129] op_sel_hi:[1,0] neg_lo:[0,1] neg_hi:[0,1]
	v_pk_mul_f32 v[120:121], v[76:77], v[76:77]
	v_add_f32_e32 v130, 0, v120
	v_add_f32_e32 v130, v121, v130
	v_pk_mul_f32 v[120:121], v[78:79], v[78:79]
	v_add_f32_e32 v130, v120, v130
	v_add_f32_e32 v130, v121, v130
	v_pk_mul_f32 v[120:121], v[80:81], v[80:81]
	v_add_f32_e32 v130, v120, v130
	v_add_f32_e32 v130, v121, v130
	v_pk_mul_f32 v[120:121], v[82:83], v[82:83]
	v_add_f32_e32 v130, v120, v130
	v_add_f32_e32 v130, v121, v130
	v_lshlrev_b32_e32 v120, 16, v52
	v_and_b32_e32 v121, 0xffff0000, v52
	v_lshlrev_b32_e32 v122, 16, v56
	v_and_b32_e32 v123, 0xffff0000, v56
	v_pk_add_f32 v[120:121], v[120:121], -1.0 op_sel_hi:[1,0]
	v_pk_add_f32 v[122:123], v[122:123], -1.0 op_sel_hi:[1,0]
; DI unsigned pack2(float a, float b) { unsigned r; asm volatile("v_cvt_pk_bf16_f32 %0, %1, %2" : "=v"(r) : "v"(a), "v"(b)); return r; }
; DI float red8(float x) { x += dppf<0xB1>(x); x += dppf<0x4E>(x); x += dppf<0x141>(x); return x; }
; DN void rw_finish_tile(const Params& p, int l, int tile, char* smem) {
;     ...
;     for (int e = 0; e < 8; ++e) {
;       const float dl = y0[e] - mean; y0[e] = dl; sv += dl * dl;
;       const float kds = kx[e] * (1.f + (af[e] - 1.f) * kaw[e]) + kx[e] * (1.f + (ab[e] - 1.f) * kaw[e]);
;       sd += rr[e] * rk[e] * kds;
;     }
;     const float var = red8(sv) * (1.f / 64.f);
;     const float sdot = red8(sd);
;     const float rs = rsqrtf(var + 64e-5f);
;     float ov[8];
; #pragma unroll
;     for (int e = 0; e < 8; ++e) ov[e] = (y0[e] * rs * lng[e] + lnb[e] + sdot * vx[e]) * gt[e];
;     u32x4 ow; ow.x = pack2(ov[0], ov[1]); ow.y = pack2(ov[2], ov[3]); ow.z = pack2(ov[4], ov[5]); ow.w = pack2(ov[6], ov[7]);
;     *(u32x4*)(O + (size_t)m * DM + c0) = ow;
;   }
	v_pk_fma_f32 v[120:121], v[88:89], v[120:121], 1.0 op_sel_hi:[1,1,0]
	v_pk_fma_f32 v[122:123], v[88:89], v[122:123], 1.0 op_sel_hi:[1,1,0]
	v_pk_mul_f32 v[120:121], v[120:121], v[104:105]
	v_pk_fma_f32 v[122:123], v[122:123], v[104:105], v[120:121]
	v_pk_mul_f32 v[124:125], v[172:173], v[96:97]
	v_pk_mul_f32 v[124:125], v[124:125], v[122:123]
	v_add_f32_e32 v131, 0, v124
	v_add_f32_e32 v131, v125, v131
	v_lshlrev_b32_e32 v120, 16, v53
	v_and_b32_e32 v121, 0xffff0000, v53
	v_lshlrev_b32_e32 v122, 16, v57
	v_and_b32_e32 v123, 0xffff0000, v57
	v_pk_add_f32 v[120:121], v[120:121], -1.0 op_sel_hi:[1,0]
	v_pk_add_f32 v[122:123], v[122:123], -1.0 op_sel_hi:[1,0]
	v_pk_fma_f32 v[120:121], v[90:91], v[120:121], 1.0 op_sel_hi:[1,1,0]
	v_pk_fma_f32 v[122:123], v[90:91], v[122:123], 1.0 op_sel_hi:[1,1,0]
	v_pk_mul_f32 v[120:121], v[120:121], v[106:107]
	v_pk_fma_f32 v[122:123], v[122:123], v[106:107], v[120:121]
	v_pk_mul_f32 v[124:125], v[174:175], v[98:99]
	v_pk_mul_f32 v[124:125], v[124:125], v[122:123]
	v_add_f32_e32 v131, v124, v131
	v_add_f32_e32 v131, v125, v131
	v_lshlrev_b32_e32 v120, 16, v54
	v_and_b32_e32 v121, 0xffff0000, v54
	v_lshlrev_b32_e32 v122, 16, v58
	v_and_b32_e32 v123, 0xffff0000, v58
	v_pk_add_f32 v[120:121], v[120:121], -1.0 op_sel_hi:[1,0]
	v_pk_add_f32 v[122:123], v[122:123], -1.0 op_sel_hi:[1,0]
	v_pk_fma_f32 v[120:121], v[92:93], v[120:121], 1.0 op_sel_hi:[1,1,0]
	v_pk_fma_f32 v[122:123], v[92:93], v[122:123], 1.0 op_sel_hi:[1,1,0]
	v_pk_mul_f32 v[120:121], v[120:121], v[108:109]
	v_pk_fma_f32 v[122:123], v[122:123], v[108:109], v[120:121]
	v_pk_mul_f32 v[124:125], v[176:177], v[100:101]
	v_pk_mul_f32 v[124:125], v[124:125], v[122:123]
	v_add_f32_e32 v131, v124, v131
	v_add_f32_e32 v131, v125, v131
	v_lshlrev_b32_e32 v120, 16, v55
	v_and_b32_e32 v121, 0xffff0000, v55
	v_lshlrev_b32_e32 v122, 16, v59
	v_and_b32_e32 v123, 0xffff0000, v59
	v_pk_add_f32 v[120:121], v[120:121], -1.0 op_sel_hi:[1,0]
	v_pk_add_f32 v[122:123], v[122:123], -1.0 op_sel_hi:[1,0]
	v_pk_fma_f32 v[120:121], v[94:95], v[120:121], 1.0 op_sel_hi:[1,1,0]
	v_pk_fma_f32 v[122:123], v[94:95], v[122:123], 1.0 op_sel_hi:[1,1,0]
	v_pk_mul_f32 v[120:121], v[120:121], v[110:111]
	v_pk_fma_f32 v[122:123], v[122:123], v[110:111], v[120:121]
	v_pk_mul_f32 v[124:125], v[178:179], v[102:103]
	v_pk_mul_f32 v[124:125], v[124:125], v[122:123]
	v_add_f32_e32 v131, v124, v131
	v_add_f32_e32 v131, v125, v131
	v_add_f32_dpp v130, v130, v130 quad_perm:[1,0,3,2] row_mask:0xf bank_mask:0xf bound_ctrl:1
	s_nop 0
	v_add_f32_dpp v131, v131, v131 quad_perm:[1,0,3,2] row_mask:0xf bank_mask:0xf bound_ctrl:1
	v_add_f32_dpp v130, v130, v130 quad_perm:[2,3,0,1] row_mask:0xf bank_mask:0xf bound_ctrl:1
	s_nop 0
	v_add_f32_dpp v131, v131, v131 quad_perm:[2,3,0,1] row_mask:0xf bank_mask:0xf bound_ctrl:1
	v_add_f32_dpp v130, v130, v130 row_half_mirror row_mask:0xf bank_mask:0xf bound_ctrl:1
	s_nop 0
	v_add_f32_dpp v131, v131, v131 row_half_mirror row_mask:0xf bank_mask:0xf bound_ctrl:1
	v_mov_b32_e32 v129, 0x3a27c5ac
	v_fmamk_f32 v130, v130, 0x3c800000, v129
	v_rsq_f32_e32 v130, v130
	v_mov_b32_e32 v126, v131
	v_pk_mul_f32 v[120:121], v[76:77], v[130:131] op_sel_hi:[1,0]
	v_pk_mul_f32 v[120:121], v[156:157], v[120:121]
	v_pk_add_f32 v[120:121], v[164:165], v[120:121]
	v_pk_mul_f32 v[122:123], v[112:113], v[126:127] op_sel_hi:[1,0]
	v_pk_add_f32 v[120:121], v[122:123], v[120:121]
	v_lshlrev_b32_e32 v122, 16, v60
	v_and_b32_e32 v123, 0xffff0000, v60
	v_pk_mul_f32 v[120:121], v[120:121], v[122:123]
	v_cvt_pk_bf16_f32 v60, v120, v121
	v_pk_mul_f32 v[120:121], v[78:79], v[130:131] op_sel_hi:[1,0]
	v_pk_mul_f32 v[120:121], v[158:159], v[120:121]
	v_pk_add_f32 v[120:121], v[166:167], v[120:121]
	v_pk_mul_f32 v[122:123], v[114:115], v[126:127] op_sel_hi:[1,0]
	v_pk_add_f32 v[120:121], v[122:123], v[120:121]
	v_lshlrev_b32_e32 v122, 16, v61
	v_and_b32_e32 v123, 0xffff0000, v61
	v_pk_mul_f32 v[120:121], v[120:121], v[122:123]
	v_cvt_pk_bf16_f32 v61, v120, v121
	v_pk_mul_f32 v[120:121], v[80:81], v[130:131] op_sel_hi:[1,0]
	v_pk_mul_f32 v[120:121], v[160:161], v[120:121]
	v_pk_add_f32 v[120:121], v[168:169], v[120:121]
	v_pk_mul_f32 v[122:123], v[116:117], v[126:127] op_sel_hi:[1,0]
	v_pk_add_f32 v[120:121], v[122:123], v[120:121]
	v_lshlrev_b32_e32 v122, 16, v62
	v_and_b32_e32 v123, 0xffff0000, v62
	v_pk_mul_f32 v[120:121], v[120:121], v[122:123]
	v_cvt_pk_bf16_f32 v62, v120, v121
	v_pk_mul_f32 v[120:121], v[82:83], v[130:131] op_sel_hi:[1,0]
	v_pk_mul_f32 v[120:121], v[162:163], v[120:121]
	v_pk_add_f32 v[120:121], v[170:171], v[120:121]
	v_pk_mul_f32 v[122:123], v[118:119], v[126:127] op_sel_hi:[1,0]
	v_pk_add_f32 v[120:121], v[122:123], v[120:121]
	v_lshlrev_b32_e32 v122, 16, v63
	v_and_b32_e32 v123, 0xffff0000, v63
	v_pk_mul_f32 v[120:121], v[120:121], v[122:123]
	v_cvt_pk_bf16_f32 v63, v120, v121
	global_store_dwordx4 v134, v[60:63], s[2:3] offset:2048
	s_branch .LBB0_1000
